# GEMM tile scheduler: division by the row-group size takes a shift/mask fast path when the group is full (exact), on top of feature-paired scan write
# speedup vs baseline: 1.0073x; 1.0056x over previous
;     __device__ bool next(int i, Unit& u) const {
;     ...
;         int wgid = (int)L; { const int q = nwg / NXCD, r = nwg % NXCD, xcd = wgid % NXCD, off = wgid / NXCD; wgid = (xcd < r ? xcd * (q + 1) : r * (q + 1) + (xcd - r) * q) + off; }
;         const int nig = WGM * nN, gid = wgid / nig, fm = gid * WGM, gsz = (nM - fm) < WGM ? (nM - fm) : WGM;
;         u.pm = fm + ((wgid % nig) % gsz); u.pn = (wgid % nig) / gsz; return true;
.LBB0_94:
	s_ashr_i32 s0, s0, 3
	s_add_i32 s0, s58, s0
	s_abs_i32 s40, s0
	s_mul_hi_u32 s41, s40, s87
	s_mul_i32 s58, s41, s83
	s_ashr_i32 s1, s0, 31
	s_sub_i32 s40, s40, s58
	s_xor_b32 s1, s1, s86
	s_add_i32 s58, s41, 1
	s_sub_i32 s63, s40, s83
	s_cmp_ge_u32 s40, s83
	s_cselect_b32 s41, s58, s41
	s_cselect_b32 s40, s63, s40
	s_add_i32 s58, s41, 1
	s_cmp_ge_u32 s40, s83
	s_cselect_b32 s40, s58, s41
	s_xor_b32 s40, s40, s1
	s_sub_i32 s1, s40, s1
	s_lshl_b32 s40, s1, 3
	s_sub_i32 s41, s73, s40
	s_min_i32 s41, s41, 8
	s_cmp_eq_u32 s41, 8
	s_cbranch_scc0 .Lsched_slow_pl
	s_mul_i32 s1, s1, s82
	s_sub_i32 s0, s0, s1
	s_ashr_i32 s63, s0, 3
	s_and_b32 s0, s0, 7
	s_add_i32 s58, s0, s40
	s_branch .LBB0_95
.Lsched_slow_pl:
	s_abs_i32 s58, s41
	v_cvt_f32_u32_e32 v0, s58
	s_sub_i32 s65, 0, s58
	s_mul_i32 s1, s1, s82
	s_sub_i32 s0, s0, s1
	v_rcp_iflag_f32_e32 v0, v0
	s_abs_i32 s63, s0
	s_xor_b32 s1, s0, s41
	s_ashr_i32 s1, s1, 31
	v_mul_f32_e32 v0, 0x4f7ffffe, v0
	v_cvt_u32_f32_e32 v0, v0
	s_nop 0
	v_readfirstlane_b32 s96, v0
	s_mul_i32 s65, s65, s96
	s_mul_hi_u32 s65, s96, s65
	s_add_i32 s96, s96, s65
	s_mul_hi_u32 s65, s63, s96
	s_mul_i32 s96, s65, s58
	s_sub_i32 s63, s63, s96
	s_add_i32 s96, s65, 1
	s_sub_i32 vcc_lo, s63, s58
	s_cmp_ge_u32 s63, s58
	s_cselect_b32 s65, s96, s65
	s_cselect_b32 s63, vcc_lo, s63
	s_add_i32 s96, s65, 1
	s_cmp_ge_u32 s63, s58
	s_cselect_b32 s58, s96, s65
	s_xor_b32 s58, s58, s1
	s_sub_i32 s63, s58, s1
	s_mul_i32 s1, s63, s41
	s_sub_i32 s0, s0, s1
	s_add_i32 s58, s0, s40

;     __device__ bool next(int i, Unit& u) const {
;         const long L = (long)i * G + c; if (L >= nwg) return false;
;         int wgid = (int)L; { const int q = nwg / NXCD, r = nwg % NXCD, xcd = wgid % NXCD, off = wgid / NXCD; wgid = (xcd < r ? xcd * (q + 1) : r * (q + 1) + (xcd - r) * q) + off; }
;         const int nig = WGM * nN, gid = wgid / nig, fm = gid * WGM, gsz = (nM - fm) < WGM ? (nM - fm) : WGM;
;         u.pm = fm + ((wgid % nig) % gsz); u.pn = (wgid % nig) / gsz; return true;
.LBB0_112:
	s_add_i32 s51, s51, 1
	s_mul_i32 s0, s51, s56
	s_mul_hi_u32 s1, s51, s3
	s_add_i32 s1, s1, s0
	s_mul_i32 s0, s51, s3
	s_add_u32 s28, s0, s69
	s_addc_u32 s29, s1, s46
	v_cmp_gt_i64_e64 s[36:37], s[28:29], v[156:157]
	s_and_b64 vcc, exec, s[36:37]
	s_cbranch_vccnz .LBB0_114
	s_ashr_i32 s0, s28, 31
	s_lshr_b32 s0, s0, 29
	s_add_i32 s0, s28, s0
	s_ashr_i32 s1, s0, 3
	s_and_b32 s0, s0, -8
	s_sub_i32 s0, s28, s0
	s_cmp_lt_i32 s0, 0
	s_movk_i32 s14, 0x161
	s_cselect_b32 s14, s14, 0x160
	s_mul_i32 s0, s0, s14
	s_add_i32 s0, s0, s1
	s_mul_hi_i32 s1, s0, 0x2e8ba2e9
	s_lshr_b32 s14, s1, 31
	s_ashr_i32 s1, s1, 5
	s_add_i32 s1, s1, s14
	s_lshl_b32 s15, s1, 3
	s_sub_i32 s14, 0x80, s15
	s_min_i32 s17, s14, 8
	s_cmp_eq_u32 s17, 8
	s_cbranch_scc0 .Lsched_slow_sw
	s_mulk_i32 s1, 0xb0
	s_sub_i32 s0, s0, s1
	s_ashr_i32 s14, s0, 3
	s_and_b32 s0, s0, 7
	s_add_i32 s24, s15, s0
	s_branch .LBB0_114
.Lsched_slow_sw:
	s_abs_i32 s14, s17
	v_cvt_f32_u32_e32 v0, s14
	s_sub_i32 s25, 0, s14
	s_mulk_i32 s1, 0xb0
	s_sub_i32 s0, s0, s1
	v_rcp_iflag_f32_e32 v0, v0
	s_abs_i32 s1, s0
	s_xor_b32 s24, s0, s17
	s_ashr_i32 s24, s24, 31
	v_mul_f32_e32 v0, 0x4f7ffffe, v0
	v_cvt_u32_f32_e32 v0, v0
	s_nop 0
	v_readfirstlane_b32 s30, v0
	s_mul_i32 s25, s25, s30
	s_mul_hi_u32 s25, s30, s25
	s_add_i32 s30, s30, s25
	s_mul_hi_u32 s25, s1, s30
	s_mul_i32 s30, s25, s14
	s_sub_i32 s1, s1, s30
	s_add_i32 s31, s25, 1
	s_sub_i32 s30, s1, s14
	s_cmp_ge_u32 s1, s14
	s_cselect_b32 s25, s31, s25
	s_cselect_b32 s1, s30, s1
	s_add_i32 s30, s25, 1
	s_cmp_ge_u32 s1, s14
	s_cselect_b32 s1, s30, s25
	s_xor_b32 s1, s1, s24
	s_sub_i32 s14, s1, s24
	s_mul_i32 s1, s14, s17
	s_sub_i32 s0, s0, s1
	s_add_i32 s24, s15, s0
